# P2d re-scan loop hand-pipelined: 16 rows in flight per wave with counted vmcnt, batched carry-in prefix (was one serialized round trip per row)
# speedup vs baseline: 1.0232x; 1.0232x over previous
; __device__ __forceinline__ unsigned cvt_pk_bf16(float lo, float hi) { unsigned r; asm volatile("v_cvt_pk_bf16_f32 %0, %1, %2" : "=v"(r) : "v"(lo), "v"(hi)); return r; }
; __device__ __forceinline__ float bf_lo(unsigned w) { return __uint_as_float(w << 16); }
; __device__ __forceinline__ float bf_hi(unsigned w) { return __uint_as_float(w & 0xffff0000u); }
; __global__ void __launch_bounds__(NTHR, 2) hybrid_block_fwd(Args a) {
;     ...
;         const int c2 = gtid & 1023, chunk = (gtid >> 10) & (NCH - 1), b = gtid >> 16;
;         f32x2 H = (f32x2){0.f, 0.f};
; #pragma unroll 4
;         for (int j = 0; j < chunk; ++j) { const f32x2 P = ((const f32x2*)(AGGP + (size_t)(b * NCH + j) * LW))[c2], Hj = ((const f32x2*)(AGGH + (size_t)(b * NCH + j) * LW))[c2]; H = P * H + Hj; }
;         const size_t r0 = (size_t)b * SEQ + (size_t)chunk * CH_L;
;         const u32x2* pab = (const u32x2*)((const unsigned*)AF + r0 * LW) + c2;
;         const unsigned* pg = (const unsigned*)(GELU_U + r0 * LW) + c2; unsigned* po = (unsigned*)(YCAT + r0 * KC + PW) + c2;
; #pragma unroll 16
;         for (int i = 0; i < CH_L; ++i) {
;             const u32x2 q = pab[(size_t)i * (LW / 2)]; const f32x2 av = (f32x2){__builtin_amdgcn_exp2f(bf_lo(q.x)), __builtin_amdgcn_exp2f(bf_lo(q.y))}, bv = (f32x2){bf_hi(q.x), bf_hi(q.y)}; const unsigned gq = pg[(size_t)i * (LW / 2)];
;             H = av * H + bv;
;             po[(size_t)i * (KC / 2)] = cvt_pk_bf16(H.x * bf_lo(gq), H.y * bf_hi(gq));
.LBB0_669:
	s_or_b64 exec, exec, s[8:9]
	s_waitcnt lgkmcnt(0)
	v_mov_b32_e32 v0, v212
	v_readlane_b32 s8, v248, 8
	s_barrier
	v_add_u32_e32 v1, s8, v0
	v_and_b32_e32 v1, 0x3ff, v1
	v_lshlrev_b32_e32 v2, 3, v1
	v_lshlrev_b32_e32 v3, 2, v1
	v_add_u32_e32 v6, 0x100000, v2
	s_lshr_b32 s9, s8, 10
	s_and_b32 s10, s9, 63
	s_lshr_b32 s11, s9, 6
	s_lshl_b32 s21, s9, 20
	s_add_u32 s12, s92, s21
	s_addc_u32 s13, s93, 0
	s_lshl_b32 s21, s9, 19
	s_add_u32 s14, s94, s21
	s_addc_u32 s15, s95, 0
	s_add_u32 s14, s14, 0x9f00000
	s_addc_u32 s15, s15, 0
	s_mul_i32 s21, s9, 0xc0000
	s_add_u32 s18, s94, s21
	s_addc_u32 s19, s95, 0
	s_add_u32 s18, s18, 0x15f00800
	s_addc_u32 s19, s19, 0
	s_lshl_b32 s21, s11, 19
	s_add_u32 s0, s94, s21
	s_addc_u32 s1, s95, 0
	s_add_u32 s0, s0, 0x100000
	s_addc_u32 s1, s1, 0
	global_load_dwordx2 v[32:33], v2, s[12:13]
	global_load_dword v64, v3, s[14:15]
	s_add_u32 s12, s12, 0x2000
	s_addc_u32 s13, s13, 0
	s_add_u32 s14, s14, 0x1000
	s_addc_u32 s15, s15, 0
	global_load_dwordx2 v[34:35], v2, s[12:13]
	global_load_dword v65, v3, s[14:15]
	s_add_u32 s12, s12, 0x2000
	s_addc_u32 s13, s13, 0
	s_add_u32 s14, s14, 0x1000
	s_addc_u32 s15, s15, 0
	global_load_dwordx2 v[36:37], v2, s[12:13]
	global_load_dword v66, v3, s[14:15]
	s_add_u32 s12, s12, 0x2000
	s_addc_u32 s13, s13, 0
	s_add_u32 s14, s14, 0x1000
	s_addc_u32 s15, s15, 0
	global_load_dwordx2 v[38:39], v2, s[12:13]
	global_load_dword v67, v3, s[14:15]
	s_add_u32 s12, s12, 0x2000
	s_addc_u32 s13, s13, 0
	s_add_u32 s14, s14, 0x1000
	s_addc_u32 s15, s15, 0
	global_load_dwordx2 v[40:41], v2, s[12:13]
	global_load_dword v68, v3, s[14:15]
	s_add_u32 s12, s12, 0x2000
	s_addc_u32 s13, s13, 0
	s_add_u32 s14, s14, 0x1000
	s_addc_u32 s15, s15, 0
	global_load_dwordx2 v[42:43], v2, s[12:13]
	global_load_dword v69, v3, s[14:15]
	s_add_u32 s12, s12, 0x2000
	s_addc_u32 s13, s13, 0
	s_add_u32 s14, s14, 0x1000
	s_addc_u32 s15, s15, 0
	global_load_dwordx2 v[44:45], v2, s[12:13]
	global_load_dword v70, v3, s[14:15]
	s_add_u32 s12, s12, 0x2000
	s_addc_u32 s13, s13, 0
	s_add_u32 s14, s14, 0x1000
	s_addc_u32 s15, s15, 0
	global_load_dwordx2 v[46:47], v2, s[12:13]
	global_load_dword v71, v3, s[14:15]
	s_add_u32 s12, s12, 0x2000
	s_addc_u32 s13, s13, 0
	s_add_u32 s14, s14, 0x1000
	s_addc_u32 s15, s15, 0
	global_load_dwordx2 v[48:49], v2, s[12:13]
	global_load_dword v72, v3, s[14:15]
	s_add_u32 s12, s12, 0x2000
	s_addc_u32 s13, s13, 0
	s_add_u32 s14, s14, 0x1000
	s_addc_u32 s15, s15, 0
	global_load_dwordx2 v[50:51], v2, s[12:13]
	global_load_dword v73, v3, s[14:15]
	s_add_u32 s12, s12, 0x2000
	s_addc_u32 s13, s13, 0
	s_add_u32 s14, s14, 0x1000
	s_addc_u32 s15, s15, 0
	global_load_dwordx2 v[52:53], v2, s[12:13]
	global_load_dword v74, v3, s[14:15]
	s_add_u32 s12, s12, 0x2000
	s_addc_u32 s13, s13, 0
	s_add_u32 s14, s14, 0x1000
	s_addc_u32 s15, s15, 0
	global_load_dwordx2 v[54:55], v2, s[12:13]
	global_load_dword v75, v3, s[14:15]
	s_add_u32 s12, s12, 0x2000
	s_addc_u32 s13, s13, 0
	s_add_u32 s14, s14, 0x1000
	s_addc_u32 s15, s15, 0
	global_load_dwordx2 v[56:57], v2, s[12:13]
	global_load_dword v76, v3, s[14:15]
	s_add_u32 s12, s12, 0x2000
	s_addc_u32 s13, s13, 0
	s_add_u32 s14, s14, 0x1000
	s_addc_u32 s15, s15, 0
	global_load_dwordx2 v[58:59], v2, s[12:13]
	global_load_dword v77, v3, s[14:15]
	s_add_u32 s12, s12, 0x2000
	s_addc_u32 s13, s13, 0
	s_add_u32 s14, s14, 0x1000
	s_addc_u32 s15, s15, 0
	global_load_dwordx2 v[60:61], v2, s[12:13]
	global_load_dword v78, v3, s[14:15]
	s_add_u32 s12, s12, 0x2000
	s_addc_u32 s13, s13, 0
	s_add_u32 s14, s14, 0x1000
	s_addc_u32 s15, s15, 0
	global_load_dwordx2 v[62:63], v2, s[12:13]
	global_load_dword v79, v3, s[14:15]
	s_add_u32 s12, s12, 0x2000
	s_addc_u32 s13, s13, 0
	s_add_u32 s14, s14, 0x1000
	s_addc_u32 s15, s15, 0
	v_mov_b32_e32 v4, 0
	v_mov_b32_e32 v5, 0
	s_cmp_eq_u32 s10, 0
	s_cbranch_scc1 .Lp2d_prefix_done
.Lp2d_prefix_batch:
	global_load_dwordx2 v[100:101], v2, s[0:1]
	global_load_dwordx2 v[102:103], v6, s[0:1]
	s_add_u32 s0, s0, 0x2000
	s_addc_u32 s1, s1, 0
	global_load_dwordx2 v[104:105], v2, s[0:1]
	global_load_dwordx2 v[106:107], v6, s[0:1]
	s_add_u32 s0, s0, 0x2000
	s_addc_u32 s1, s1, 0
	global_load_dwordx2 v[108:109], v2, s[0:1]
	global_load_dwordx2 v[110:111], v6, s[0:1]
	s_add_u32 s0, s0, 0x2000
	s_addc_u32 s1, s1, 0
	global_load_dwordx2 v[112:113], v2, s[0:1]
	global_load_dwordx2 v[114:115], v6, s[0:1]
	s_add_u32 s0, s0, 0x2000
	s_addc_u32 s1, s1, 0
	global_load_dwordx2 v[116:117], v2, s[0:1]
	global_load_dwordx2 v[118:119], v6, s[0:1]
	s_add_u32 s0, s0, 0x2000
	s_addc_u32 s1, s1, 0
	global_load_dwordx2 v[120:121], v2, s[0:1]
	global_load_dwordx2 v[122:123], v6, s[0:1]
	s_add_u32 s0, s0, 0x2000
	s_addc_u32 s1, s1, 0
	global_load_dwordx2 v[124:125], v2, s[0:1]
	global_load_dwordx2 v[126:127], v6, s[0:1]
	s_add_u32 s0, s0, 0x2000
	s_addc_u32 s1, s1, 0
	global_load_dwordx2 v[128:129], v2, s[0:1]
	global_load_dwordx2 v[130:131], v6, s[0:1]
	s_add_u32 s0, s0, 0x2000
	s_addc_u32 s1, s1, 0
	global_load_dwordx2 v[132:133], v2, s[0:1]
	global_load_dwordx2 v[134:135], v6, s[0:1]
	s_add_u32 s0, s0, 0x2000
	s_addc_u32 s1, s1, 0
	global_load_dwordx2 v[136:137], v2, s[0:1]
	global_load_dwordx2 v[138:139], v6, s[0:1]
	s_add_u32 s0, s0, 0x2000
	s_addc_u32 s1, s1, 0
	global_load_dwordx2 v[140:141], v2, s[0:1]
	global_load_dwordx2 v[142:143], v6, s[0:1]
	s_add_u32 s0, s0, 0x2000
	s_addc_u32 s1, s1, 0
	global_load_dwordx2 v[144:145], v2, s[0:1]
	global_load_dwordx2 v[146:147], v6, s[0:1]
	s_add_u32 s0, s0, 0x2000
	s_addc_u32 s1, s1, 0
	global_load_dwordx2 v[148:149], v2, s[0:1]
	global_load_dwordx2 v[150:151], v6, s[0:1]
	s_add_u32 s0, s0, 0x2000
	s_addc_u32 s1, s1, 0
	global_load_dwordx2 v[152:153], v2, s[0:1]
	global_load_dwordx2 v[154:155], v6, s[0:1]
	s_add_u32 s0, s0, 0x2000
	s_addc_u32 s1, s1, 0
	global_load_dwordx2 v[156:157], v2, s[0:1]
	global_load_dwordx2 v[158:159], v6, s[0:1]
	s_add_u32 s0, s0, 0x2000
	s_addc_u32 s1, s1, 0
	global_load_dwordx2 v[160:161], v2, s[0:1]
	global_load_dwordx2 v[162:163], v6, s[0:1]
	s_add_u32 s0, s0, 0x2000
	s_addc_u32 s1, s1, 0
	s_waitcnt vmcnt(30)
	v_pk_fma_f32 v[4:5], v[4:5], v[100:101], v[102:103]
	s_sub_u32 s10, s10, 1
	s_cmp_eq_u32 s10, 0
	s_cbranch_scc1 .Lp2d_prefix_done
; __device__ __forceinline__ unsigned cvt_pk_bf16(float lo, float hi) { unsigned r; asm volatile("v_cvt_pk_bf16_f32 %0, %1, %2" : "=v"(r) : "v"(lo), "v"(hi)); return r; }
; __device__ __forceinline__ float bf_lo(unsigned w) { return __uint_as_float(w << 16); }
; __device__ __forceinline__ float bf_hi(unsigned w) { return __uint_as_float(w & 0xffff0000u); }
; __global__ void __launch_bounds__(NTHR, 2) hybrid_block_fwd(Args a) {
;     ...
;         for (int j = 0; j < chunk; ++j) { const f32x2 P = ((const f32x2*)(AGGP + (size_t)(b * NCH + j) * LW))[c2], Hj = ((const f32x2*)(AGGH + (size_t)(b * NCH + j) * LW))[c2]; H = P * H + Hj; }
;         const size_t r0 = (size_t)b * SEQ + (size_t)chunk * CH_L;
;         const u32x2* pab = (const u32x2*)((const unsigned*)AF + r0 * LW) + c2;
;         const unsigned* pg = (const unsigned*)(GELU_U + r0 * LW) + c2; unsigned* po = (unsigned*)(YCAT + r0 * KC + PW) + c2;
; #pragma unroll 16
;         for (int i = 0; i < CH_L; ++i) {
;             const u32x2 q = pab[(size_t)i * (LW / 2)]; const f32x2 av = (f32x2){__builtin_amdgcn_exp2f(bf_lo(q.x)), __builtin_amdgcn_exp2f(bf_lo(q.y))}, bv = (f32x2){bf_hi(q.x), bf_hi(q.y)}; const unsigned gq = pg[(size_t)i * (LW / 2)];
;             H = av * H + bv;
;             po[(size_t)i * (KC / 2)] = cvt_pk_bf16(H.x * bf_lo(gq), H.y * bf_hi(gq));
	s_waitcnt vmcnt(28)
	v_pk_fma_f32 v[4:5], v[4:5], v[104:105], v[106:107]
	s_sub_u32 s10, s10, 1
	s_cmp_eq_u32 s10, 0
	s_cbranch_scc1 .Lp2d_prefix_done
	s_waitcnt vmcnt(26)
	v_pk_fma_f32 v[4:5], v[4:5], v[108:109], v[110:111]
	s_sub_u32 s10, s10, 1
	s_cmp_eq_u32 s10, 0
	s_cbranch_scc1 .Lp2d_prefix_done
	s_waitcnt vmcnt(24)
	v_pk_fma_f32 v[4:5], v[4:5], v[112:113], v[114:115]
	s_sub_u32 s10, s10, 1
	s_cmp_eq_u32 s10, 0
	s_cbranch_scc1 .Lp2d_prefix_done
	s_waitcnt vmcnt(22)
	v_pk_fma_f32 v[4:5], v[4:5], v[116:117], v[118:119]
	s_sub_u32 s10, s10, 1
	s_cmp_eq_u32 s10, 0
	s_cbranch_scc1 .Lp2d_prefix_done
	s_waitcnt vmcnt(20)
	v_pk_fma_f32 v[4:5], v[4:5], v[120:121], v[122:123]
	s_sub_u32 s10, s10, 1
	s_cmp_eq_u32 s10, 0
	s_cbranch_scc1 .Lp2d_prefix_done
	s_waitcnt vmcnt(18)
	v_pk_fma_f32 v[4:5], v[4:5], v[124:125], v[126:127]
	s_sub_u32 s10, s10, 1
	s_cmp_eq_u32 s10, 0
	s_cbranch_scc1 .Lp2d_prefix_done
	s_waitcnt vmcnt(16)
	v_pk_fma_f32 v[4:5], v[4:5], v[128:129], v[130:131]
	s_sub_u32 s10, s10, 1
	s_cmp_eq_u32 s10, 0
	s_cbranch_scc1 .Lp2d_prefix_done
	s_waitcnt vmcnt(14)
	v_pk_fma_f32 v[4:5], v[4:5], v[132:133], v[134:135]
	s_sub_u32 s10, s10, 1
	s_cmp_eq_u32 s10, 0
	s_cbranch_scc1 .Lp2d_prefix_done
	s_waitcnt vmcnt(12)
	v_pk_fma_f32 v[4:5], v[4:5], v[136:137], v[138:139]
	s_sub_u32 s10, s10, 1
	s_cmp_eq_u32 s10, 0
	s_cbranch_scc1 .Lp2d_prefix_done
	s_waitcnt vmcnt(10)
	v_pk_fma_f32 v[4:5], v[4:5], v[140:141], v[142:143]
	s_sub_u32 s10, s10, 1
	s_cmp_eq_u32 s10, 0
	s_cbranch_scc1 .Lp2d_prefix_done
	s_waitcnt vmcnt(8)
	v_pk_fma_f32 v[4:5], v[4:5], v[144:145], v[146:147]
	s_sub_u32 s10, s10, 1
	s_cmp_eq_u32 s10, 0
	s_cbranch_scc1 .Lp2d_prefix_done
	s_waitcnt vmcnt(6)
	v_pk_fma_f32 v[4:5], v[4:5], v[148:149], v[150:151]
	s_sub_u32 s10, s10, 1
	s_cmp_eq_u32 s10, 0
	s_cbranch_scc1 .Lp2d_prefix_done
	s_waitcnt vmcnt(4)
	v_pk_fma_f32 v[4:5], v[4:5], v[152:153], v[154:155]
	s_sub_u32 s10, s10, 1
	s_cmp_eq_u32 s10, 0
	s_cbranch_scc1 .Lp2d_prefix_done
	s_waitcnt vmcnt(2)
	v_pk_fma_f32 v[4:5], v[4:5], v[156:157], v[158:159]
	s_sub_u32 s10, s10, 1
	s_cmp_eq_u32 s10, 0
	s_cbranch_scc1 .Lp2d_prefix_done
	s_waitcnt vmcnt(0)
	v_pk_fma_f32 v[4:5], v[4:5], v[160:161], v[162:163]
	s_sub_u32 s10, s10, 1
	s_cmp_eq_u32 s10, 0
	s_cbranch_scc1 .Lp2d_prefix_done
	s_branch .Lp2d_prefix_batch
.Lp2d_prefix_done:
	s_waitcnt vmcnt(30)
	v_lshlrev_b32_e32 v8, 16, v32
	v_lshlrev_b32_e32 v9, 16, v33
	v_exp_f32_e32 v8, v8
	v_exp_f32_e32 v9, v9
	v_and_b32_e32 v10, 0xffff0000, v32
	v_and_b32_e32 v11, 0xffff0000, v33
	v_lshlrev_b32_e32 v12, 16, v64
	v_and_b32_e32 v13, 0xffff0000, v64
	v_pk_fma_f32 v[4:5], v[4:5], v[8:9], v[10:11]
	v_mul_f32_e32 v12, v4, v12
	v_mul_f32_e32 v13, v5, v13
	v_cvt_pk_bf16_f32 v12, v12, v13
	global_store_dword v3, v12, s[18:19]
	s_add_u32 s18, s18, 0x1800
	s_addc_u32 s19, s19, 0
	global_load_dwordx2 v[32:33], v2, s[12:13]
	global_load_dword v64, v3, s[14:15]
	s_add_u32 s12, s12, 0x2000
	s_addc_u32 s13, s13, 0
	s_add_u32 s14, s14, 0x1000
	s_addc_u32 s15, s15, 0
	s_waitcnt vmcnt(31)
	v_lshlrev_b32_e32 v16, 16, v34
	v_lshlrev_b32_e32 v17, 16, v35
	v_exp_f32_e32 v16, v16
	v_exp_f32_e32 v17, v17
	v_and_b32_e32 v18, 0xffff0000, v34
	v_and_b32_e32 v19, 0xffff0000, v35
	v_lshlrev_b32_e32 v20, 16, v65
	v_and_b32_e32 v21, 0xffff0000, v65
	v_pk_fma_f32 v[4:5], v[4:5], v[16:17], v[18:19]
	v_mul_f32_e32 v20, v4, v20
	v_mul_f32_e32 v21, v5, v21
	v_cvt_pk_bf16_f32 v20, v20, v21
	global_store_dword v3, v20, s[18:19]
	s_add_u32 s18, s18, 0x1800
	s_addc_u32 s19, s19, 0
	global_load_dwordx2 v[34:35], v2, s[12:13]
	global_load_dword v65, v3, s[14:15]
	s_add_u32 s12, s12, 0x2000
	s_addc_u32 s13, s13, 0
	s_add_u32 s14, s14, 0x1000
	s_addc_u32 s15, s15, 0
	s_waitcnt vmcnt(32)
	v_lshlrev_b32_e32 v8, 16, v36
	v_lshlrev_b32_e32 v9, 16, v37
	v_exp_f32_e32 v8, v8
	v_exp_f32_e32 v9, v9
	v_and_b32_e32 v10, 0xffff0000, v36
	v_and_b32_e32 v11, 0xffff0000, v37
	v_lshlrev_b32_e32 v12, 16, v66
	v_and_b32_e32 v13, 0xffff0000, v66
	v_pk_fma_f32 v[4:5], v[4:5], v[8:9], v[10:11]
	v_mul_f32_e32 v12, v4, v12
	v_mul_f32_e32 v13, v5, v13
	v_cvt_pk_bf16_f32 v12, v12, v13
	global_store_dword v3, v12, s[18:19]
	s_add_u32 s18, s18, 0x1800
	s_addc_u32 s19, s19, 0
	global_load_dwordx2 v[36:37], v2, s[12:13]
	global_load_dword v66, v3, s[14:15]
	s_add_u32 s12, s12, 0x2000
	s_addc_u32 s13, s13, 0
	s_add_u32 s14, s14, 0x1000
	s_addc_u32 s15, s15, 0
	s_waitcnt vmcnt(33)
	v_lshlrev_b32_e32 v16, 16, v38
	v_lshlrev_b32_e32 v17, 16, v39
	v_exp_f32_e32 v16, v16
	v_exp_f32_e32 v17, v17
	v_and_b32_e32 v18, 0xffff0000, v38
	v_and_b32_e32 v19, 0xffff0000, v39
	v_lshlrev_b32_e32 v20, 16, v67
	v_and_b32_e32 v21, 0xffff0000, v67
	v_pk_fma_f32 v[4:5], v[4:5], v[16:17], v[18:19]
	v_mul_f32_e32 v20, v4, v20
	v_mul_f32_e32 v21, v5, v21
	v_cvt_pk_bf16_f32 v20, v20, v21
	global_store_dword v3, v20, s[18:19]
	s_add_u32 s18, s18, 0x1800
	s_addc_u32 s19, s19, 0
	global_load_dwordx2 v[38:39], v2, s[12:13]
	global_load_dword v67, v3, s[14:15]
	s_add_u32 s12, s12, 0x2000
	s_addc_u32 s13, s13, 0
	s_add_u32 s14, s14, 0x1000
	s_addc_u32 s15, s15, 0
	s_waitcnt vmcnt(34)
	v_lshlrev_b32_e32 v8, 16, v40
	v_lshlrev_b32_e32 v9, 16, v41
	v_exp_f32_e32 v8, v8
	v_exp_f32_e32 v9, v9
	v_and_b32_e32 v10, 0xffff0000, v40
	v_and_b32_e32 v11, 0xffff0000, v41
	v_lshlrev_b32_e32 v12, 16, v68
	v_and_b32_e32 v13, 0xffff0000, v68
	v_pk_fma_f32 v[4:5], v[4:5], v[8:9], v[10:11]
	v_mul_f32_e32 v12, v4, v12
	v_mul_f32_e32 v13, v5, v13
	v_cvt_pk_bf16_f32 v12, v12, v13
	global_store_dword v3, v12, s[18:19]
	s_add_u32 s18, s18, 0x1800
	s_addc_u32 s19, s19, 0
	global_load_dwordx2 v[40:41], v2, s[12:13]
	global_load_dword v68, v3, s[14:15]
	s_add_u32 s12, s12, 0x2000
	s_addc_u32 s13, s13, 0
	s_add_u32 s14, s14, 0x1000
	s_addc_u32 s15, s15, 0
	s_waitcnt vmcnt(35)
; __device__ __forceinline__ unsigned cvt_pk_bf16(float lo, float hi) { unsigned r; asm volatile("v_cvt_pk_bf16_f32 %0, %1, %2" : "=v"(r) : "v"(lo), "v"(hi)); return r; }
; __device__ __forceinline__ float bf_lo(unsigned w) { return __uint_as_float(w << 16); }
; __device__ __forceinline__ float bf_hi(unsigned w) { return __uint_as_float(w & 0xffff0000u); }
; __global__ void __launch_bounds__(NTHR, 2) hybrid_block_fwd(Args a) {
;     ...
;         for (int i = 0; i < CH_L; ++i) {
;             const u32x2 q = pab[(size_t)i * (LW / 2)]; const f32x2 av = (f32x2){__builtin_amdgcn_exp2f(bf_lo(q.x)), __builtin_amdgcn_exp2f(bf_lo(q.y))}, bv = (f32x2){bf_hi(q.x), bf_hi(q.y)}; const unsigned gq = pg[(size_t)i * (LW / 2)];
;             H = av * H + bv;
;             po[(size_t)i * (KC / 2)] = cvt_pk_bf16(H.x * bf_lo(gq), H.y * bf_hi(gq));
	v_lshlrev_b32_e32 v16, 16, v42
	v_lshlrev_b32_e32 v17, 16, v43
	v_exp_f32_e32 v16, v16
	v_exp_f32_e32 v17, v17
	v_and_b32_e32 v18, 0xffff0000, v42
	v_and_b32_e32 v19, 0xffff0000, v43
	v_lshlrev_b32_e32 v20, 16, v69
	v_and_b32_e32 v21, 0xffff0000, v69
	v_pk_fma_f32 v[4:5], v[4:5], v[16:17], v[18:19]
	v_mul_f32_e32 v20, v4, v20
	v_mul_f32_e32 v21, v5, v21
	v_cvt_pk_bf16_f32 v20, v20, v21
	global_store_dword v3, v20, s[18:19]
	s_add_u32 s18, s18, 0x1800
	s_addc_u32 s19, s19, 0
	global_load_dwordx2 v[42:43], v2, s[12:13]
	global_load_dword v69, v3, s[14:15]
	s_add_u32 s12, s12, 0x2000
	s_addc_u32 s13, s13, 0
	s_add_u32 s14, s14, 0x1000
	s_addc_u32 s15, s15, 0
	s_waitcnt vmcnt(36)
	v_lshlrev_b32_e32 v8, 16, v44
	v_lshlrev_b32_e32 v9, 16, v45
	v_exp_f32_e32 v8, v8
	v_exp_f32_e32 v9, v9
	v_and_b32_e32 v10, 0xffff0000, v44
	v_and_b32_e32 v11, 0xffff0000, v45
	v_lshlrev_b32_e32 v12, 16, v70
	v_and_b32_e32 v13, 0xffff0000, v70
	v_pk_fma_f32 v[4:5], v[4:5], v[8:9], v[10:11]
	v_mul_f32_e32 v12, v4, v12
	v_mul_f32_e32 v13, v5, v13
	v_cvt_pk_bf16_f32 v12, v12, v13
	global_store_dword v3, v12, s[18:19]
	s_add_u32 s18, s18, 0x1800
	s_addc_u32 s19, s19, 0
	global_load_dwordx2 v[44:45], v2, s[12:13]
	global_load_dword v70, v3, s[14:15]
	s_add_u32 s12, s12, 0x2000
	s_addc_u32 s13, s13, 0
	s_add_u32 s14, s14, 0x1000
	s_addc_u32 s15, s15, 0
	s_waitcnt vmcnt(37)
	v_lshlrev_b32_e32 v16, 16, v46
	v_lshlrev_b32_e32 v17, 16, v47
	v_exp_f32_e32 v16, v16
	v_exp_f32_e32 v17, v17
	v_and_b32_e32 v18, 0xffff0000, v46
	v_and_b32_e32 v19, 0xffff0000, v47
	v_lshlrev_b32_e32 v20, 16, v71
	v_and_b32_e32 v21, 0xffff0000, v71
	v_pk_fma_f32 v[4:5], v[4:5], v[16:17], v[18:19]
	v_mul_f32_e32 v20, v4, v20
	v_mul_f32_e32 v21, v5, v21
	v_cvt_pk_bf16_f32 v20, v20, v21
	global_store_dword v3, v20, s[18:19]
	s_add_u32 s18, s18, 0x1800
	s_addc_u32 s19, s19, 0
	global_load_dwordx2 v[46:47], v2, s[12:13]
	global_load_dword v71, v3, s[14:15]
	s_add_u32 s12, s12, 0x2000
	s_addc_u32 s13, s13, 0
	s_add_u32 s14, s14, 0x1000
	s_addc_u32 s15, s15, 0
	s_waitcnt vmcnt(38)
	v_lshlrev_b32_e32 v8, 16, v48
	v_lshlrev_b32_e32 v9, 16, v49
	v_exp_f32_e32 v8, v8
	v_exp_f32_e32 v9, v9
	v_and_b32_e32 v10, 0xffff0000, v48
	v_and_b32_e32 v11, 0xffff0000, v49
	v_lshlrev_b32_e32 v12, 16, v72
	v_and_b32_e32 v13, 0xffff0000, v72
	v_pk_fma_f32 v[4:5], v[4:5], v[8:9], v[10:11]
	v_mul_f32_e32 v12, v4, v12
	v_mul_f32_e32 v13, v5, v13
	v_cvt_pk_bf16_f32 v12, v12, v13
	global_store_dword v3, v12, s[18:19]
	s_add_u32 s18, s18, 0x1800
	s_addc_u32 s19, s19, 0
	global_load_dwordx2 v[48:49], v2, s[12:13]
	global_load_dword v72, v3, s[14:15]
	s_add_u32 s12, s12, 0x2000
	s_addc_u32 s13, s13, 0
	s_add_u32 s14, s14, 0x1000
	s_addc_u32 s15, s15, 0
	s_waitcnt vmcnt(39)
	v_lshlrev_b32_e32 v16, 16, v50
	v_lshlrev_b32_e32 v17, 16, v51
	v_exp_f32_e32 v16, v16
	v_exp_f32_e32 v17, v17
	v_and_b32_e32 v18, 0xffff0000, v50
	v_and_b32_e32 v19, 0xffff0000, v51
	v_lshlrev_b32_e32 v20, 16, v73
	v_and_b32_e32 v21, 0xffff0000, v73
	v_pk_fma_f32 v[4:5], v[4:5], v[16:17], v[18:19]
	v_mul_f32_e32 v20, v4, v20
	v_mul_f32_e32 v21, v5, v21
	v_cvt_pk_bf16_f32 v20, v20, v21
	global_store_dword v3, v20, s[18:19]
	s_add_u32 s18, s18, 0x1800
	s_addc_u32 s19, s19, 0
	global_load_dwordx2 v[50:51], v2, s[12:13]
	global_load_dword v73, v3, s[14:15]
	s_add_u32 s12, s12, 0x2000
	s_addc_u32 s13, s13, 0
	s_add_u32 s14, s14, 0x1000
	s_addc_u32 s15, s15, 0
	s_waitcnt vmcnt(40)
	v_lshlrev_b32_e32 v8, 16, v52
	v_lshlrev_b32_e32 v9, 16, v53
	v_exp_f32_e32 v8, v8
	v_exp_f32_e32 v9, v9
	v_and_b32_e32 v10, 0xffff0000, v52
	v_and_b32_e32 v11, 0xffff0000, v53
	v_lshlrev_b32_e32 v12, 16, v74
	v_and_b32_e32 v13, 0xffff0000, v74
	v_pk_fma_f32 v[4:5], v[4:5], v[8:9], v[10:11]
	v_mul_f32_e32 v12, v4, v12
	v_mul_f32_e32 v13, v5, v13
	v_cvt_pk_bf16_f32 v12, v12, v13
	global_store_dword v3, v12, s[18:19]
	s_add_u32 s18, s18, 0x1800
	s_addc_u32 s19, s19, 0
	global_load_dwordx2 v[52:53], v2, s[12:13]
	global_load_dword v74, v3, s[14:15]
	s_add_u32 s12, s12, 0x2000
	s_addc_u32 s13, s13, 0
	s_add_u32 s14, s14, 0x1000
	s_addc_u32 s15, s15, 0
	s_waitcnt vmcnt(41)
	v_lshlrev_b32_e32 v16, 16, v54
	v_lshlrev_b32_e32 v17, 16, v55
	v_exp_f32_e32 v16, v16
	v_exp_f32_e32 v17, v17
	v_and_b32_e32 v18, 0xffff0000, v54
	v_and_b32_e32 v19, 0xffff0000, v55
	v_lshlrev_b32_e32 v20, 16, v75
	v_and_b32_e32 v21, 0xffff0000, v75
	v_pk_fma_f32 v[4:5], v[4:5], v[16:17], v[18:19]
	v_mul_f32_e32 v20, v4, v20
	v_mul_f32_e32 v21, v5, v21
	v_cvt_pk_bf16_f32 v20, v20, v21
	global_store_dword v3, v20, s[18:19]
	s_add_u32 s18, s18, 0x1800
	s_addc_u32 s19, s19, 0
	global_load_dwordx2 v[54:55], v2, s[12:13]
	global_load_dword v75, v3, s[14:15]
	s_add_u32 s12, s12, 0x2000
	s_addc_u32 s13, s13, 0
	s_add_u32 s14, s14, 0x1000
	s_addc_u32 s15, s15, 0
	s_waitcnt vmcnt(42)
	v_lshlrev_b32_e32 v8, 16, v56
	v_lshlrev_b32_e32 v9, 16, v57
	v_exp_f32_e32 v8, v8
	v_exp_f32_e32 v9, v9
	v_and_b32_e32 v10, 0xffff0000, v56
	v_and_b32_e32 v11, 0xffff0000, v57
	v_lshlrev_b32_e32 v12, 16, v76
	v_and_b32_e32 v13, 0xffff0000, v76
	v_pk_fma_f32 v[4:5], v[4:5], v[8:9], v[10:11]
	v_mul_f32_e32 v12, v4, v12
	v_mul_f32_e32 v13, v5, v13
	v_cvt_pk_bf16_f32 v12, v12, v13
	global_store_dword v3, v12, s[18:19]
	s_add_u32 s18, s18, 0x1800
	s_addc_u32 s19, s19, 0
	global_load_dwordx2 v[56:57], v2, s[12:13]
	global_load_dword v76, v3, s[14:15]
	s_add_u32 s12, s12, 0x2000
	s_addc_u32 s13, s13, 0
	s_add_u32 s14, s14, 0x1000
	s_addc_u32 s15, s15, 0
	s_waitcnt vmcnt(43)
; __device__ __forceinline__ unsigned cvt_pk_bf16(float lo, float hi) { unsigned r; asm volatile("v_cvt_pk_bf16_f32 %0, %1, %2" : "=v"(r) : "v"(lo), "v"(hi)); return r; }
; __device__ __forceinline__ float bf_lo(unsigned w) { return __uint_as_float(w << 16); }
; __device__ __forceinline__ float bf_hi(unsigned w) { return __uint_as_float(w & 0xffff0000u); }
; __global__ void __launch_bounds__(NTHR, 2) hybrid_block_fwd(Args a) {
;     ...
;         for (int i = 0; i < CH_L; ++i) {
;             const u32x2 q = pab[(size_t)i * (LW / 2)]; const f32x2 av = (f32x2){__builtin_amdgcn_exp2f(bf_lo(q.x)), __builtin_amdgcn_exp2f(bf_lo(q.y))}, bv = (f32x2){bf_hi(q.x), bf_hi(q.y)}; const unsigned gq = pg[(size_t)i * (LW / 2)];
;             H = av * H + bv;
;             po[(size_t)i * (KC / 2)] = cvt_pk_bf16(H.x * bf_lo(gq), H.y * bf_hi(gq));
	v_lshlrev_b32_e32 v16, 16, v58
	v_lshlrev_b32_e32 v17, 16, v59
	v_exp_f32_e32 v16, v16
	v_exp_f32_e32 v17, v17
	v_and_b32_e32 v18, 0xffff0000, v58
	v_and_b32_e32 v19, 0xffff0000, v59
	v_lshlrev_b32_e32 v20, 16, v77
	v_and_b32_e32 v21, 0xffff0000, v77
	v_pk_fma_f32 v[4:5], v[4:5], v[16:17], v[18:19]
	v_mul_f32_e32 v20, v4, v20
	v_mul_f32_e32 v21, v5, v21
	v_cvt_pk_bf16_f32 v20, v20, v21
	global_store_dword v3, v20, s[18:19]
	s_add_u32 s18, s18, 0x1800
	s_addc_u32 s19, s19, 0
	global_load_dwordx2 v[58:59], v2, s[12:13]
	global_load_dword v77, v3, s[14:15]
	s_add_u32 s12, s12, 0x2000
	s_addc_u32 s13, s13, 0
	s_add_u32 s14, s14, 0x1000
	s_addc_u32 s15, s15, 0
	s_waitcnt vmcnt(44)
	v_lshlrev_b32_e32 v8, 16, v60
	v_lshlrev_b32_e32 v9, 16, v61
	v_exp_f32_e32 v8, v8
	v_exp_f32_e32 v9, v9
	v_and_b32_e32 v10, 0xffff0000, v60
	v_and_b32_e32 v11, 0xffff0000, v61
	v_lshlrev_b32_e32 v12, 16, v78
	v_and_b32_e32 v13, 0xffff0000, v78
	v_pk_fma_f32 v[4:5], v[4:5], v[8:9], v[10:11]
	v_mul_f32_e32 v12, v4, v12
	v_mul_f32_e32 v13, v5, v13
	v_cvt_pk_bf16_f32 v12, v12, v13
	global_store_dword v3, v12, s[18:19]
	s_add_u32 s18, s18, 0x1800
	s_addc_u32 s19, s19, 0
	global_load_dwordx2 v[60:61], v2, s[12:13]
	global_load_dword v78, v3, s[14:15]
	s_add_u32 s12, s12, 0x2000
	s_addc_u32 s13, s13, 0
	s_add_u32 s14, s14, 0x1000
	s_addc_u32 s15, s15, 0
	s_waitcnt vmcnt(45)
	v_lshlrev_b32_e32 v16, 16, v62
	v_lshlrev_b32_e32 v17, 16, v63
	v_exp_f32_e32 v16, v16
	v_exp_f32_e32 v17, v17
	v_and_b32_e32 v18, 0xffff0000, v62
	v_and_b32_e32 v19, 0xffff0000, v63
	v_lshlrev_b32_e32 v20, 16, v79
	v_and_b32_e32 v21, 0xffff0000, v79
	v_pk_fma_f32 v[4:5], v[4:5], v[16:17], v[18:19]
	v_mul_f32_e32 v20, v4, v20
	v_mul_f32_e32 v21, v5, v21
	v_cvt_pk_bf16_f32 v20, v20, v21
	global_store_dword v3, v20, s[18:19]
	s_add_u32 s18, s18, 0x1800
	s_addc_u32 s19, s19, 0
	global_load_dwordx2 v[62:63], v2, s[12:13]
	global_load_dword v79, v3, s[14:15]
	s_add_u32 s12, s12, 0x2000
	s_addc_u32 s13, s13, 0
	s_add_u32 s14, s14, 0x1000
	s_addc_u32 s15, s15, 0
	s_mov_b32 s22, 6
.Lp2d_steady:
	s_waitcnt vmcnt(45)
	v_lshlrev_b32_e32 v8, 16, v32
	v_lshlrev_b32_e32 v9, 16, v33
	v_exp_f32_e32 v8, v8
	v_exp_f32_e32 v9, v9
	v_and_b32_e32 v10, 0xffff0000, v32
	v_and_b32_e32 v11, 0xffff0000, v33
	v_lshlrev_b32_e32 v12, 16, v64
	v_and_b32_e32 v13, 0xffff0000, v64
	v_pk_fma_f32 v[4:5], v[4:5], v[8:9], v[10:11]
	v_mul_f32_e32 v12, v4, v12
	v_mul_f32_e32 v13, v5, v13
	v_cvt_pk_bf16_f32 v12, v12, v13
	global_store_dword v3, v12, s[18:19]
	s_add_u32 s18, s18, 0x1800
	s_addc_u32 s19, s19, 0
	global_load_dwordx2 v[32:33], v2, s[12:13]
	global_load_dword v64, v3, s[14:15]
	s_add_u32 s12, s12, 0x2000
	s_addc_u32 s13, s13, 0
	s_add_u32 s14, s14, 0x1000
	s_addc_u32 s15, s15, 0
	s_waitcnt vmcnt(45)
	v_lshlrev_b32_e32 v16, 16, v34
	v_lshlrev_b32_e32 v17, 16, v35
	v_exp_f32_e32 v16, v16
	v_exp_f32_e32 v17, v17
	v_and_b32_e32 v18, 0xffff0000, v34
	v_and_b32_e32 v19, 0xffff0000, v35
	v_lshlrev_b32_e32 v20, 16, v65
	v_and_b32_e32 v21, 0xffff0000, v65
	v_pk_fma_f32 v[4:5], v[4:5], v[16:17], v[18:19]
	v_mul_f32_e32 v20, v4, v20
	v_mul_f32_e32 v21, v5, v21
	v_cvt_pk_bf16_f32 v20, v20, v21
	global_store_dword v3, v20, s[18:19]
	s_add_u32 s18, s18, 0x1800
	s_addc_u32 s19, s19, 0
	global_load_dwordx2 v[34:35], v2, s[12:13]
	global_load_dword v65, v3, s[14:15]
	s_add_u32 s12, s12, 0x2000
	s_addc_u32 s13, s13, 0
	s_add_u32 s14, s14, 0x1000
	s_addc_u32 s15, s15, 0
	s_waitcnt vmcnt(45)
	v_lshlrev_b32_e32 v8, 16, v36
	v_lshlrev_b32_e32 v9, 16, v37
	v_exp_f32_e32 v8, v8
	v_exp_f32_e32 v9, v9
	v_and_b32_e32 v10, 0xffff0000, v36
	v_and_b32_e32 v11, 0xffff0000, v37
	v_lshlrev_b32_e32 v12, 16, v66
	v_and_b32_e32 v13, 0xffff0000, v66
	v_pk_fma_f32 v[4:5], v[4:5], v[8:9], v[10:11]
	v_mul_f32_e32 v12, v4, v12
	v_mul_f32_e32 v13, v5, v13
	v_cvt_pk_bf16_f32 v12, v12, v13
	global_store_dword v3, v12, s[18:19]
	s_add_u32 s18, s18, 0x1800
	s_addc_u32 s19, s19, 0
	global_load_dwordx2 v[36:37], v2, s[12:13]
	global_load_dword v66, v3, s[14:15]
	s_add_u32 s12, s12, 0x2000
	s_addc_u32 s13, s13, 0
	s_add_u32 s14, s14, 0x1000
	s_addc_u32 s15, s15, 0
	s_waitcnt vmcnt(45)
	v_lshlrev_b32_e32 v16, 16, v38
	v_lshlrev_b32_e32 v17, 16, v39
	v_exp_f32_e32 v16, v16
	v_exp_f32_e32 v17, v17
	v_and_b32_e32 v18, 0xffff0000, v38
	v_and_b32_e32 v19, 0xffff0000, v39
	v_lshlrev_b32_e32 v20, 16, v67
	v_and_b32_e32 v21, 0xffff0000, v67
	v_pk_fma_f32 v[4:5], v[4:5], v[16:17], v[18:19]
	v_mul_f32_e32 v20, v4, v20
	v_mul_f32_e32 v21, v5, v21
	v_cvt_pk_bf16_f32 v20, v20, v21
	global_store_dword v3, v20, s[18:19]
	s_add_u32 s18, s18, 0x1800
	s_addc_u32 s19, s19, 0
	global_load_dwordx2 v[38:39], v2, s[12:13]
	global_load_dword v67, v3, s[14:15]
	s_add_u32 s12, s12, 0x2000
	s_addc_u32 s13, s13, 0
	s_add_u32 s14, s14, 0x1000
	s_addc_u32 s15, s15, 0
	s_waitcnt vmcnt(45)
	v_lshlrev_b32_e32 v8, 16, v40
	v_lshlrev_b32_e32 v9, 16, v41
	v_exp_f32_e32 v8, v8
	v_exp_f32_e32 v9, v9
	v_and_b32_e32 v10, 0xffff0000, v40
	v_and_b32_e32 v11, 0xffff0000, v41
	v_lshlrev_b32_e32 v12, 16, v68
	v_and_b32_e32 v13, 0xffff0000, v68
	v_pk_fma_f32 v[4:5], v[4:5], v[8:9], v[10:11]
	v_mul_f32_e32 v12, v4, v12
	v_mul_f32_e32 v13, v5, v13
	v_cvt_pk_bf16_f32 v12, v12, v13
	global_store_dword v3, v12, s[18:19]
	s_add_u32 s18, s18, 0x1800
	s_addc_u32 s19, s19, 0
	global_load_dwordx2 v[40:41], v2, s[12:13]
	global_load_dword v68, v3, s[14:15]
	s_add_u32 s12, s12, 0x2000
	s_addc_u32 s13, s13, 0
	s_add_u32 s14, s14, 0x1000
	s_addc_u32 s15, s15, 0
	s_waitcnt vmcnt(45)
; __device__ __forceinline__ unsigned cvt_pk_bf16(float lo, float hi) { unsigned r; asm volatile("v_cvt_pk_bf16_f32 %0, %1, %2" : "=v"(r) : "v"(lo), "v"(hi)); return r; }
; __device__ __forceinline__ float bf_lo(unsigned w) { return __uint_as_float(w << 16); }
; __device__ __forceinline__ float bf_hi(unsigned w) { return __uint_as_float(w & 0xffff0000u); }
; __global__ void __launch_bounds__(NTHR, 2) hybrid_block_fwd(Args a) {
;     ...
;         for (int i = 0; i < CH_L; ++i) {
;             const u32x2 q = pab[(size_t)i * (LW / 2)]; const f32x2 av = (f32x2){__builtin_amdgcn_exp2f(bf_lo(q.x)), __builtin_amdgcn_exp2f(bf_lo(q.y))}, bv = (f32x2){bf_hi(q.x), bf_hi(q.y)}; const unsigned gq = pg[(size_t)i * (LW / 2)];
;             H = av * H + bv;
;             po[(size_t)i * (KC / 2)] = cvt_pk_bf16(H.x * bf_lo(gq), H.y * bf_hi(gq));
	v_lshlrev_b32_e32 v16, 16, v42
	v_lshlrev_b32_e32 v17, 16, v43
	v_exp_f32_e32 v16, v16
	v_exp_f32_e32 v17, v17
	v_and_b32_e32 v18, 0xffff0000, v42
	v_and_b32_e32 v19, 0xffff0000, v43
	v_lshlrev_b32_e32 v20, 16, v69
	v_and_b32_e32 v21, 0xffff0000, v69
	v_pk_fma_f32 v[4:5], v[4:5], v[16:17], v[18:19]
	v_mul_f32_e32 v20, v4, v20
	v_mul_f32_e32 v21, v5, v21
	v_cvt_pk_bf16_f32 v20, v20, v21
	global_store_dword v3, v20, s[18:19]
	s_add_u32 s18, s18, 0x1800
	s_addc_u32 s19, s19, 0
	global_load_dwordx2 v[42:43], v2, s[12:13]
	global_load_dword v69, v3, s[14:15]
	s_add_u32 s12, s12, 0x2000
	s_addc_u32 s13, s13, 0
	s_add_u32 s14, s14, 0x1000
	s_addc_u32 s15, s15, 0
	s_waitcnt vmcnt(45)
	v_lshlrev_b32_e32 v8, 16, v44
	v_lshlrev_b32_e32 v9, 16, v45
	v_exp_f32_e32 v8, v8
	v_exp_f32_e32 v9, v9
	v_and_b32_e32 v10, 0xffff0000, v44
	v_and_b32_e32 v11, 0xffff0000, v45
	v_lshlrev_b32_e32 v12, 16, v70
	v_and_b32_e32 v13, 0xffff0000, v70
	v_pk_fma_f32 v[4:5], v[4:5], v[8:9], v[10:11]
	v_mul_f32_e32 v12, v4, v12
	v_mul_f32_e32 v13, v5, v13
	v_cvt_pk_bf16_f32 v12, v12, v13
	global_store_dword v3, v12, s[18:19]
	s_add_u32 s18, s18, 0x1800
	s_addc_u32 s19, s19, 0
	global_load_dwordx2 v[44:45], v2, s[12:13]
	global_load_dword v70, v3, s[14:15]
	s_add_u32 s12, s12, 0x2000
	s_addc_u32 s13, s13, 0
	s_add_u32 s14, s14, 0x1000
	s_addc_u32 s15, s15, 0
	s_waitcnt vmcnt(45)
	v_lshlrev_b32_e32 v16, 16, v46
	v_lshlrev_b32_e32 v17, 16, v47
	v_exp_f32_e32 v16, v16
	v_exp_f32_e32 v17, v17
	v_and_b32_e32 v18, 0xffff0000, v46
	v_and_b32_e32 v19, 0xffff0000, v47
	v_lshlrev_b32_e32 v20, 16, v71
	v_and_b32_e32 v21, 0xffff0000, v71
	v_pk_fma_f32 v[4:5], v[4:5], v[16:17], v[18:19]
	v_mul_f32_e32 v20, v4, v20
	v_mul_f32_e32 v21, v5, v21
	v_cvt_pk_bf16_f32 v20, v20, v21
	global_store_dword v3, v20, s[18:19]
	s_add_u32 s18, s18, 0x1800
	s_addc_u32 s19, s19, 0
	global_load_dwordx2 v[46:47], v2, s[12:13]
	global_load_dword v71, v3, s[14:15]
	s_add_u32 s12, s12, 0x2000
	s_addc_u32 s13, s13, 0
	s_add_u32 s14, s14, 0x1000
	s_addc_u32 s15, s15, 0
	s_waitcnt vmcnt(45)
	v_lshlrev_b32_e32 v8, 16, v48
	v_lshlrev_b32_e32 v9, 16, v49
	v_exp_f32_e32 v8, v8
	v_exp_f32_e32 v9, v9
	v_and_b32_e32 v10, 0xffff0000, v48
	v_and_b32_e32 v11, 0xffff0000, v49
	v_lshlrev_b32_e32 v12, 16, v72
	v_and_b32_e32 v13, 0xffff0000, v72
	v_pk_fma_f32 v[4:5], v[4:5], v[8:9], v[10:11]
	v_mul_f32_e32 v12, v4, v12
	v_mul_f32_e32 v13, v5, v13
	v_cvt_pk_bf16_f32 v12, v12, v13
	global_store_dword v3, v12, s[18:19]
	s_add_u32 s18, s18, 0x1800
	s_addc_u32 s19, s19, 0
	global_load_dwordx2 v[48:49], v2, s[12:13]
	global_load_dword v72, v3, s[14:15]
	s_add_u32 s12, s12, 0x2000
	s_addc_u32 s13, s13, 0
	s_add_u32 s14, s14, 0x1000
	s_addc_u32 s15, s15, 0
	s_waitcnt vmcnt(45)
	v_lshlrev_b32_e32 v16, 16, v50
	v_lshlrev_b32_e32 v17, 16, v51
	v_exp_f32_e32 v16, v16
	v_exp_f32_e32 v17, v17
	v_and_b32_e32 v18, 0xffff0000, v50
	v_and_b32_e32 v19, 0xffff0000, v51
	v_lshlrev_b32_e32 v20, 16, v73
	v_and_b32_e32 v21, 0xffff0000, v73
	v_pk_fma_f32 v[4:5], v[4:5], v[16:17], v[18:19]
	v_mul_f32_e32 v20, v4, v20
	v_mul_f32_e32 v21, v5, v21
	v_cvt_pk_bf16_f32 v20, v20, v21
	global_store_dword v3, v20, s[18:19]
	s_add_u32 s18, s18, 0x1800
	s_addc_u32 s19, s19, 0
	global_load_dwordx2 v[50:51], v2, s[12:13]
	global_load_dword v73, v3, s[14:15]
	s_add_u32 s12, s12, 0x2000
	s_addc_u32 s13, s13, 0
	s_add_u32 s14, s14, 0x1000
	s_addc_u32 s15, s15, 0
	s_waitcnt vmcnt(45)
	v_lshlrev_b32_e32 v8, 16, v52
	v_lshlrev_b32_e32 v9, 16, v53
	v_exp_f32_e32 v8, v8
	v_exp_f32_e32 v9, v9
	v_and_b32_e32 v10, 0xffff0000, v52
	v_and_b32_e32 v11, 0xffff0000, v53
	v_lshlrev_b32_e32 v12, 16, v74
	v_and_b32_e32 v13, 0xffff0000, v74
	v_pk_fma_f32 v[4:5], v[4:5], v[8:9], v[10:11]
	v_mul_f32_e32 v12, v4, v12
	v_mul_f32_e32 v13, v5, v13
	v_cvt_pk_bf16_f32 v12, v12, v13
	global_store_dword v3, v12, s[18:19]
	s_add_u32 s18, s18, 0x1800
	s_addc_u32 s19, s19, 0
	global_load_dwordx2 v[52:53], v2, s[12:13]
	global_load_dword v74, v3, s[14:15]
	s_add_u32 s12, s12, 0x2000
	s_addc_u32 s13, s13, 0
	s_add_u32 s14, s14, 0x1000
	s_addc_u32 s15, s15, 0
	s_waitcnt vmcnt(45)
	v_lshlrev_b32_e32 v16, 16, v54
	v_lshlrev_b32_e32 v17, 16, v55
	v_exp_f32_e32 v16, v16
	v_exp_f32_e32 v17, v17
	v_and_b32_e32 v18, 0xffff0000, v54
	v_and_b32_e32 v19, 0xffff0000, v55
	v_lshlrev_b32_e32 v20, 16, v75
	v_and_b32_e32 v21, 0xffff0000, v75
	v_pk_fma_f32 v[4:5], v[4:5], v[16:17], v[18:19]
	v_mul_f32_e32 v20, v4, v20
	v_mul_f32_e32 v21, v5, v21
	v_cvt_pk_bf16_f32 v20, v20, v21
	global_store_dword v3, v20, s[18:19]
	s_add_u32 s18, s18, 0x1800
	s_addc_u32 s19, s19, 0
	global_load_dwordx2 v[54:55], v2, s[12:13]
	global_load_dword v75, v3, s[14:15]
	s_add_u32 s12, s12, 0x2000
	s_addc_u32 s13, s13, 0
	s_add_u32 s14, s14, 0x1000
	s_addc_u32 s15, s15, 0
	s_waitcnt vmcnt(45)
	v_lshlrev_b32_e32 v8, 16, v56
	v_lshlrev_b32_e32 v9, 16, v57
	v_exp_f32_e32 v8, v8
	v_exp_f32_e32 v9, v9
	v_and_b32_e32 v10, 0xffff0000, v56
	v_and_b32_e32 v11, 0xffff0000, v57
	v_lshlrev_b32_e32 v12, 16, v76
	v_and_b32_e32 v13, 0xffff0000, v76
	v_pk_fma_f32 v[4:5], v[4:5], v[8:9], v[10:11]
	v_mul_f32_e32 v12, v4, v12
	v_mul_f32_e32 v13, v5, v13
	v_cvt_pk_bf16_f32 v12, v12, v13
	global_store_dword v3, v12, s[18:19]
	s_add_u32 s18, s18, 0x1800
	s_addc_u32 s19, s19, 0
	global_load_dwordx2 v[56:57], v2, s[12:13]
	global_load_dword v76, v3, s[14:15]
	s_add_u32 s12, s12, 0x2000
	s_addc_u32 s13, s13, 0
	s_add_u32 s14, s14, 0x1000
	s_addc_u32 s15, s15, 0
	s_waitcnt vmcnt(45)
; __device__ __forceinline__ unsigned cvt_pk_bf16(float lo, float hi) { unsigned r; asm volatile("v_cvt_pk_bf16_f32 %0, %1, %2" : "=v"(r) : "v"(lo), "v"(hi)); return r; }
; __device__ __forceinline__ float bf_lo(unsigned w) { return __uint_as_float(w << 16); }
; __device__ __forceinline__ float bf_hi(unsigned w) { return __uint_as_float(w & 0xffff0000u); }
; __global__ void __launch_bounds__(NTHR, 2) hybrid_block_fwd(Args a) {
;     ...
;         for (int i = 0; i < CH_L; ++i) {
;             const u32x2 q = pab[(size_t)i * (LW / 2)]; const f32x2 av = (f32x2){__builtin_amdgcn_exp2f(bf_lo(q.x)), __builtin_amdgcn_exp2f(bf_lo(q.y))}, bv = (f32x2){bf_hi(q.x), bf_hi(q.y)}; const unsigned gq = pg[(size_t)i * (LW / 2)];
;             H = av * H + bv;
;             po[(size_t)i * (KC / 2)] = cvt_pk_bf16(H.x * bf_lo(gq), H.y * bf_hi(gq));
	v_lshlrev_b32_e32 v16, 16, v58
	v_lshlrev_b32_e32 v17, 16, v59
	v_exp_f32_e32 v16, v16
	v_exp_f32_e32 v17, v17
	v_and_b32_e32 v18, 0xffff0000, v58
	v_and_b32_e32 v19, 0xffff0000, v59
	v_lshlrev_b32_e32 v20, 16, v77
	v_and_b32_e32 v21, 0xffff0000, v77
	v_pk_fma_f32 v[4:5], v[4:5], v[16:17], v[18:19]
	v_mul_f32_e32 v20, v4, v20
	v_mul_f32_e32 v21, v5, v21
	v_cvt_pk_bf16_f32 v20, v20, v21
	global_store_dword v3, v20, s[18:19]
	s_add_u32 s18, s18, 0x1800
	s_addc_u32 s19, s19, 0
	global_load_dwordx2 v[58:59], v2, s[12:13]
	global_load_dword v77, v3, s[14:15]
	s_add_u32 s12, s12, 0x2000
	s_addc_u32 s13, s13, 0
	s_add_u32 s14, s14, 0x1000
	s_addc_u32 s15, s15, 0
	s_waitcnt vmcnt(45)
	v_lshlrev_b32_e32 v8, 16, v60
	v_lshlrev_b32_e32 v9, 16, v61
	v_exp_f32_e32 v8, v8
	v_exp_f32_e32 v9, v9
	v_and_b32_e32 v10, 0xffff0000, v60
	v_and_b32_e32 v11, 0xffff0000, v61
	v_lshlrev_b32_e32 v12, 16, v78
	v_and_b32_e32 v13, 0xffff0000, v78
	v_pk_fma_f32 v[4:5], v[4:5], v[8:9], v[10:11]
	v_mul_f32_e32 v12, v4, v12
	v_mul_f32_e32 v13, v5, v13
	v_cvt_pk_bf16_f32 v12, v12, v13
	global_store_dword v3, v12, s[18:19]
	s_add_u32 s18, s18, 0x1800
	s_addc_u32 s19, s19, 0
	global_load_dwordx2 v[60:61], v2, s[12:13]
	global_load_dword v78, v3, s[14:15]
	s_add_u32 s12, s12, 0x2000
	s_addc_u32 s13, s13, 0
	s_add_u32 s14, s14, 0x1000
	s_addc_u32 s15, s15, 0
	s_waitcnt vmcnt(45)
	v_lshlrev_b32_e32 v16, 16, v62
	v_lshlrev_b32_e32 v17, 16, v63
	v_exp_f32_e32 v16, v16
	v_exp_f32_e32 v17, v17
	v_and_b32_e32 v18, 0xffff0000, v62
	v_and_b32_e32 v19, 0xffff0000, v63
	v_lshlrev_b32_e32 v20, 16, v79
	v_and_b32_e32 v21, 0xffff0000, v79
	v_pk_fma_f32 v[4:5], v[4:5], v[16:17], v[18:19]
	v_mul_f32_e32 v20, v4, v20
	v_mul_f32_e32 v21, v5, v21
	v_cvt_pk_bf16_f32 v20, v20, v21
	global_store_dword v3, v20, s[18:19]
	s_add_u32 s18, s18, 0x1800
	s_addc_u32 s19, s19, 0
	global_load_dwordx2 v[62:63], v2, s[12:13]
	global_load_dword v79, v3, s[14:15]
	s_add_u32 s12, s12, 0x2000
	s_addc_u32 s13, s13, 0
	s_add_u32 s14, s14, 0x1000
	s_addc_u32 s15, s15, 0
	s_sub_u32 s22, s22, 1
	s_cmp_lg_u32 s22, 0
	s_cbranch_scc1 .Lp2d_steady
	s_waitcnt vmcnt(45)
	v_lshlrev_b32_e32 v8, 16, v32
	v_lshlrev_b32_e32 v9, 16, v33
	v_exp_f32_e32 v8, v8
	v_exp_f32_e32 v9, v9
	v_and_b32_e32 v10, 0xffff0000, v32
	v_and_b32_e32 v11, 0xffff0000, v33
	v_lshlrev_b32_e32 v12, 16, v64
	v_and_b32_e32 v13, 0xffff0000, v64
	v_pk_fma_f32 v[4:5], v[4:5], v[8:9], v[10:11]
	v_mul_f32_e32 v12, v4, v12
	v_mul_f32_e32 v13, v5, v13
	v_cvt_pk_bf16_f32 v12, v12, v13
	global_store_dword v3, v12, s[18:19]
	s_add_u32 s18, s18, 0x1800
	s_addc_u32 s19, s19, 0
	s_waitcnt vmcnt(43)
	v_lshlrev_b32_e32 v16, 16, v34
	v_lshlrev_b32_e32 v17, 16, v35
	v_exp_f32_e32 v16, v16
	v_exp_f32_e32 v17, v17
	v_and_b32_e32 v18, 0xffff0000, v34
	v_and_b32_e32 v19, 0xffff0000, v35
	v_lshlrev_b32_e32 v20, 16, v65
	v_and_b32_e32 v21, 0xffff0000, v65
	v_pk_fma_f32 v[4:5], v[4:5], v[16:17], v[18:19]
	v_mul_f32_e32 v20, v4, v20
	v_mul_f32_e32 v21, v5, v21
	v_cvt_pk_bf16_f32 v20, v20, v21
	global_store_dword v3, v20, s[18:19]
	s_add_u32 s18, s18, 0x1800
	s_addc_u32 s19, s19, 0
	s_waitcnt vmcnt(41)
	v_lshlrev_b32_e32 v8, 16, v36
	v_lshlrev_b32_e32 v9, 16, v37
	v_exp_f32_e32 v8, v8
	v_exp_f32_e32 v9, v9
	v_and_b32_e32 v10, 0xffff0000, v36
	v_and_b32_e32 v11, 0xffff0000, v37
	v_lshlrev_b32_e32 v12, 16, v66
	v_and_b32_e32 v13, 0xffff0000, v66
	v_pk_fma_f32 v[4:5], v[4:5], v[8:9], v[10:11]
	v_mul_f32_e32 v12, v4, v12
	v_mul_f32_e32 v13, v5, v13
	v_cvt_pk_bf16_f32 v12, v12, v13
	global_store_dword v3, v12, s[18:19]
	s_add_u32 s18, s18, 0x1800
	s_addc_u32 s19, s19, 0
	s_waitcnt vmcnt(39)
	v_lshlrev_b32_e32 v16, 16, v38
	v_lshlrev_b32_e32 v17, 16, v39
	v_exp_f32_e32 v16, v16
	v_exp_f32_e32 v17, v17
	v_and_b32_e32 v18, 0xffff0000, v38
	v_and_b32_e32 v19, 0xffff0000, v39
	v_lshlrev_b32_e32 v20, 16, v67
	v_and_b32_e32 v21, 0xffff0000, v67
	v_pk_fma_f32 v[4:5], v[4:5], v[16:17], v[18:19]
	v_mul_f32_e32 v20, v4, v20
	v_mul_f32_e32 v21, v5, v21
	v_cvt_pk_bf16_f32 v20, v20, v21
	global_store_dword v3, v20, s[18:19]
	s_add_u32 s18, s18, 0x1800
	s_addc_u32 s19, s19, 0
	s_waitcnt vmcnt(37)
	v_lshlrev_b32_e32 v8, 16, v40
	v_lshlrev_b32_e32 v9, 16, v41
	v_exp_f32_e32 v8, v8
	v_exp_f32_e32 v9, v9
	v_and_b32_e32 v10, 0xffff0000, v40
	v_and_b32_e32 v11, 0xffff0000, v41
	v_lshlrev_b32_e32 v12, 16, v68
	v_and_b32_e32 v13, 0xffff0000, v68
	v_pk_fma_f32 v[4:5], v[4:5], v[8:9], v[10:11]
	v_mul_f32_e32 v12, v4, v12
	v_mul_f32_e32 v13, v5, v13
	v_cvt_pk_bf16_f32 v12, v12, v13
	global_store_dword v3, v12, s[18:19]
	s_add_u32 s18, s18, 0x1800
	s_addc_u32 s19, s19, 0
	s_waitcnt vmcnt(35)
	v_lshlrev_b32_e32 v16, 16, v42
	v_lshlrev_b32_e32 v17, 16, v43
	v_exp_f32_e32 v16, v16
	v_exp_f32_e32 v17, v17
	v_and_b32_e32 v18, 0xffff0000, v42
	v_and_b32_e32 v19, 0xffff0000, v43
	v_lshlrev_b32_e32 v20, 16, v69
	v_and_b32_e32 v21, 0xffff0000, v69
	v_pk_fma_f32 v[4:5], v[4:5], v[16:17], v[18:19]
	v_mul_f32_e32 v20, v4, v20
	v_mul_f32_e32 v21, v5, v21
	v_cvt_pk_bf16_f32 v20, v20, v21
	global_store_dword v3, v20, s[18:19]
	s_add_u32 s18, s18, 0x1800
	s_addc_u32 s19, s19, 0
	s_waitcnt vmcnt(33)
	v_lshlrev_b32_e32 v8, 16, v44
	v_lshlrev_b32_e32 v9, 16, v45
	v_exp_f32_e32 v8, v8
	v_exp_f32_e32 v9, v9
	v_and_b32_e32 v10, 0xffff0000, v44
	v_and_b32_e32 v11, 0xffff0000, v45
	v_lshlrev_b32_e32 v12, 16, v70
	v_and_b32_e32 v13, 0xffff0000, v70
	v_pk_fma_f32 v[4:5], v[4:5], v[8:9], v[10:11]
	v_mul_f32_e32 v12, v4, v12
	v_mul_f32_e32 v13, v5, v13
	v_cvt_pk_bf16_f32 v12, v12, v13
	global_store_dword v3, v12, s[18:19]
	s_add_u32 s18, s18, 0x1800
	s_addc_u32 s19, s19, 0
	s_waitcnt vmcnt(31)
; __device__ __forceinline__ unsigned cvt_pk_bf16(float lo, float hi) { unsigned r; asm volatile("v_cvt_pk_bf16_f32 %0, %1, %2" : "=v"(r) : "v"(lo), "v"(hi)); return r; }
; __device__ __forceinline__ float bf_lo(unsigned w) { return __uint_as_float(w << 16); }
; __device__ __forceinline__ float bf_hi(unsigned w) { return __uint_as_float(w & 0xffff0000u); }
; __device__ __forceinline__ void xcd_barrier(const XcdBarrier& b) {
;     asm volatile("s_waitcnt vmcnt(0)" ::: "memory");
;     __syncthreads();
;     if (threadIdx.x == 0) {
;         unsigned* bar = b.bar;
;         __builtin_amdgcn_s_waitcnt(0);
;         unsigned nloc = b.st[0], nx = b.st[1];
;         if (nloc == 0u) { xcd_barrier_complete(bar, b.x, nloc, nx); b.st[0] = nloc; b.st[1] = nx; }
; __global__ void __launch_bounds__(NTHR, 2) hybrid_block_fwd(Args a) {
;     ...
;         for (int i = 0; i < CH_L; ++i) {
;             const u32x2 q = pab[(size_t)i * (LW / 2)]; const f32x2 av = (f32x2){__builtin_amdgcn_exp2f(bf_lo(q.x)), __builtin_amdgcn_exp2f(bf_lo(q.y))}, bv = (f32x2){bf_hi(q.x), bf_hi(q.y)}; const unsigned gq = pg[(size_t)i * (LW / 2)];
;             H = av * H + bv;
;             po[(size_t)i * (KC / 2)] = cvt_pk_bf16(H.x * bf_lo(gq), H.y * bf_hi(gq));
	v_lshlrev_b32_e32 v16, 16, v46
	v_lshlrev_b32_e32 v17, 16, v47
	v_exp_f32_e32 v16, v16
	v_exp_f32_e32 v17, v17
	v_and_b32_e32 v18, 0xffff0000, v46
	v_and_b32_e32 v19, 0xffff0000, v47
	v_lshlrev_b32_e32 v20, 16, v71
	v_and_b32_e32 v21, 0xffff0000, v71
	v_pk_fma_f32 v[4:5], v[4:5], v[16:17], v[18:19]
	v_mul_f32_e32 v20, v4, v20
	v_mul_f32_e32 v21, v5, v21
	v_cvt_pk_bf16_f32 v20, v20, v21
	global_store_dword v3, v20, s[18:19]
	s_add_u32 s18, s18, 0x1800
	s_addc_u32 s19, s19, 0
	s_waitcnt vmcnt(29)
	v_lshlrev_b32_e32 v8, 16, v48
	v_lshlrev_b32_e32 v9, 16, v49
	v_exp_f32_e32 v8, v8
	v_exp_f32_e32 v9, v9
	v_and_b32_e32 v10, 0xffff0000, v48
	v_and_b32_e32 v11, 0xffff0000, v49
	v_lshlrev_b32_e32 v12, 16, v72
	v_and_b32_e32 v13, 0xffff0000, v72
	v_pk_fma_f32 v[4:5], v[4:5], v[8:9], v[10:11]
	v_mul_f32_e32 v12, v4, v12
	v_mul_f32_e32 v13, v5, v13
	v_cvt_pk_bf16_f32 v12, v12, v13
	global_store_dword v3, v12, s[18:19]
	s_add_u32 s18, s18, 0x1800
	s_addc_u32 s19, s19, 0
	s_waitcnt vmcnt(27)
	v_lshlrev_b32_e32 v16, 16, v50
	v_lshlrev_b32_e32 v17, 16, v51
	v_exp_f32_e32 v16, v16
	v_exp_f32_e32 v17, v17
	v_and_b32_e32 v18, 0xffff0000, v50
	v_and_b32_e32 v19, 0xffff0000, v51
	v_lshlrev_b32_e32 v20, 16, v73
	v_and_b32_e32 v21, 0xffff0000, v73
	v_pk_fma_f32 v[4:5], v[4:5], v[16:17], v[18:19]
	v_mul_f32_e32 v20, v4, v20
	v_mul_f32_e32 v21, v5, v21
	v_cvt_pk_bf16_f32 v20, v20, v21
	global_store_dword v3, v20, s[18:19]
	s_add_u32 s18, s18, 0x1800
	s_addc_u32 s19, s19, 0
	s_waitcnt vmcnt(25)
	v_lshlrev_b32_e32 v8, 16, v52
	v_lshlrev_b32_e32 v9, 16, v53
	v_exp_f32_e32 v8, v8
	v_exp_f32_e32 v9, v9
	v_and_b32_e32 v10, 0xffff0000, v52
	v_and_b32_e32 v11, 0xffff0000, v53
	v_lshlrev_b32_e32 v12, 16, v74
	v_and_b32_e32 v13, 0xffff0000, v74
	v_pk_fma_f32 v[4:5], v[4:5], v[8:9], v[10:11]
	v_mul_f32_e32 v12, v4, v12
	v_mul_f32_e32 v13, v5, v13
	v_cvt_pk_bf16_f32 v12, v12, v13
	global_store_dword v3, v12, s[18:19]
	s_add_u32 s18, s18, 0x1800
	s_addc_u32 s19, s19, 0
	s_waitcnt vmcnt(23)
	v_lshlrev_b32_e32 v16, 16, v54
	v_lshlrev_b32_e32 v17, 16, v55
	v_exp_f32_e32 v16, v16
	v_exp_f32_e32 v17, v17
	v_and_b32_e32 v18, 0xffff0000, v54
	v_and_b32_e32 v19, 0xffff0000, v55
	v_lshlrev_b32_e32 v20, 16, v75
	v_and_b32_e32 v21, 0xffff0000, v75
	v_pk_fma_f32 v[4:5], v[4:5], v[16:17], v[18:19]
	v_mul_f32_e32 v20, v4, v20
	v_mul_f32_e32 v21, v5, v21
	v_cvt_pk_bf16_f32 v20, v20, v21
	global_store_dword v3, v20, s[18:19]
	s_add_u32 s18, s18, 0x1800
	s_addc_u32 s19, s19, 0
	s_waitcnt vmcnt(21)
	v_lshlrev_b32_e32 v8, 16, v56
	v_lshlrev_b32_e32 v9, 16, v57
	v_exp_f32_e32 v8, v8
	v_exp_f32_e32 v9, v9
	v_and_b32_e32 v10, 0xffff0000, v56
	v_and_b32_e32 v11, 0xffff0000, v57
	v_lshlrev_b32_e32 v12, 16, v76
	v_and_b32_e32 v13, 0xffff0000, v76
	v_pk_fma_f32 v[4:5], v[4:5], v[8:9], v[10:11]
	v_mul_f32_e32 v12, v4, v12
	v_mul_f32_e32 v13, v5, v13
	v_cvt_pk_bf16_f32 v12, v12, v13
	global_store_dword v3, v12, s[18:19]
	s_add_u32 s18, s18, 0x1800
	s_addc_u32 s19, s19, 0
	s_waitcnt vmcnt(19)
	v_lshlrev_b32_e32 v16, 16, v58
	v_lshlrev_b32_e32 v17, 16, v59
	v_exp_f32_e32 v16, v16
	v_exp_f32_e32 v17, v17
	v_and_b32_e32 v18, 0xffff0000, v58
	v_and_b32_e32 v19, 0xffff0000, v59
	v_lshlrev_b32_e32 v20, 16, v77
	v_and_b32_e32 v21, 0xffff0000, v77
	v_pk_fma_f32 v[4:5], v[4:5], v[16:17], v[18:19]
	v_mul_f32_e32 v20, v4, v20
	v_mul_f32_e32 v21, v5, v21
	v_cvt_pk_bf16_f32 v20, v20, v21
	global_store_dword v3, v20, s[18:19]
	s_add_u32 s18, s18, 0x1800
	s_addc_u32 s19, s19, 0
	s_waitcnt vmcnt(17)
	v_lshlrev_b32_e32 v8, 16, v60
	v_lshlrev_b32_e32 v9, 16, v61
	v_exp_f32_e32 v8, v8
	v_exp_f32_e32 v9, v9
	v_and_b32_e32 v10, 0xffff0000, v60
	v_and_b32_e32 v11, 0xffff0000, v61
	v_lshlrev_b32_e32 v12, 16, v78
	v_and_b32_e32 v13, 0xffff0000, v78
	v_pk_fma_f32 v[4:5], v[4:5], v[8:9], v[10:11]
	v_mul_f32_e32 v12, v4, v12
	v_mul_f32_e32 v13, v5, v13
	v_cvt_pk_bf16_f32 v12, v12, v13
	global_store_dword v3, v12, s[18:19]
	s_add_u32 s18, s18, 0x1800
	s_addc_u32 s19, s19, 0
	s_waitcnt vmcnt(15)
	v_lshlrev_b32_e32 v16, 16, v62
	v_lshlrev_b32_e32 v17, 16, v63
	v_exp_f32_e32 v16, v16
	v_exp_f32_e32 v17, v17
	v_and_b32_e32 v18, 0xffff0000, v62
	v_and_b32_e32 v19, 0xffff0000, v63
	v_lshlrev_b32_e32 v20, 16, v79
	v_and_b32_e32 v21, 0xffff0000, v79
	v_pk_fma_f32 v[4:5], v[4:5], v[16:17], v[18:19]
	v_mul_f32_e32 v20, v4, v20
	v_mul_f32_e32 v21, v5, v21
	v_cvt_pk_bf16_f32 v20, v20, v21
	global_store_dword v3, v20, s[18:19]
	s_add_u32 s18, s18, 0x1800
	s_addc_u32 s19, s19, 0
	s_waitcnt vmcnt(0)
	s_barrier
	s_mov_b64 s[0:1], exec
	v_readlane_b32 s4, v248, 6
	v_readlane_b32 s5, v248, 7
	s_and_b64 s[4:5], s[0:1], s[4:5]
	s_mov_b64 exec, s[4:5]
	s_cbranch_execz .LBB0_735
	s_add_i32 s4, 0, 0x20020
	v_mov_b32_e32 v0, s4
	s_waitcnt vmcnt(0) expcnt(0) lgkmcnt(0)
	ds_read_b32 v2, v0
	s_add_i32 s4, 0, 0x20024
	v_mov_b32_e32 v0, s4
	ds_read_b32 v0, v0
	s_waitcnt lgkmcnt(1)
	v_cmp_ne_u32_e32 vcc, 0, v2
	s_cbranch_vccnz .LBB0_699
	v_readlane_b32 s4, v248, 2
	v_readlane_b32 s5, v248, 3
	v_readlane_b32 s8, v248, 1
	s_mul_i32 s18, s5, s8
	s_mul_i32 s18, s18, s4
	s_add_u32 s4, s94, 0x40200
	s_addc_u32 s5, s95, 0
	s_add_u32 s8, s94, 0x40400
	s_addc_u32 s9, s95, 0
	s_add_u32 s10, s94, 0x40500
	s_addc_u32 s11, s95, 0
	s_add_u32 s38, s94, 0x40600
	s_addc_u32 s39, s95, 0
	s_add_u32 s42, s94, 0x40700
	s_addc_u32 s43, s95, 0
	s_add_u32 s54, s94, 0x40800
	s_addc_u32 s55, s95, 0
	s_add_u32 s56, s94, 0x40900
	s_addc_u32 s57, s95, 0
	s_add_u32 s58, s94, 0x40a00
	s_addc_u32 s59, s95, 0
	s_add_u32 s60, s94, 0x40b00
	s_addc_u32 s61, s95, 0
	s_add_u32 s62, s94, 0x40c00
	s_addc_u32 s63, s95, 0
	s_add_u32 s64, s94, 0x40d00
	s_addc_u32 s65, s95, 0
	s_add_u32 s66, s94, 0x40e00
	s_addc_u32 s67, s95, 0
	s_add_u32 s70, s94, 0x40f00
	s_addc_u32 s71, s95, 0
	s_add_u32 s72, s94, 0x41000
	s_addc_u32 s73, s95, 0
	s_add_u32 s74, s94, 0x41100
	s_addc_u32 s75, s95, 0
	s_add_u32 s34, s94, 0x41200
	s_addc_u32 s35, s95, 0
	s_add_u32 s48, s94, 0x41300
	s_addc_u32 s49, s95, 0
	s_mov_b32 s19, 1
	v_mov_b32_e32 v16, 0
	s_branch .LBB0_687
